# same as previous role-split version but the forgetting-attention loop raises s_setprio 1 around role B's MFMA block (as the differential loop does)
# speedup vs baseline: 1.0046x; 1.0046x over previous
; __device__ __forceinline__ s16x4 vtr(ldsp p) { return __builtin_bit_cast(s16x4, __builtin_amdgcn_ds_read_tr16_b64_v4i16((LAS v4i16_t*)p)); }
; #define MASK_BLOCK() do { if (kt == 0 || kt >= diag0) { \
;             _Pragma("unroll") for (int r = 0; r < 16; ++r) { const int kpp = 64 * kt + crow(r, hi); \
;                 if (kpp < 48 || kpp > q_pp) s0[r] = -INFINITY; \
;                 if (kpp + 32 < 48 || kpp + 32 > q_pp) s1[r] = -INFINITY; } } } while (0)
; #define EXPSUM_BLOCK() do { psa = 0.f; psb = 0.f; \
;             _Pragma("unroll") for (int r = 0; r < 16; ++r) { s0[r] = __builtin_amdgcn_exp2f(s0[r]); s1[r] = __builtin_amdgcn_exp2f(s1[r]); psa += s0[r]; asm("" : "+v"(psa)); psb += s1[r]; asm("" : "+v"(psb)); } } while (0)
; template <bool DIFF>
; __device__ __forceinline__ void attn_unit(const AttnP& A, int b, int h, int qi, ldsp lds) {
;     ...
;             QK_BLOCK();
;             s16x4 vlo[8], vhi[8];
; #pragma unroll
;             for (int t = 0; t < 2; ++t)
; #pragma unroll
;                 for (int j = 0; j < 4; ++j) { vlo[t * 4 + j] = vtr(Vb + trb + (16 * j) * VP + t * 64); vhi[t * 4 + j] = vtr(Vb + trb + (16 * j + 8) * VP + t * 64); }
;             __builtin_amdgcn_sched_barrier(0);
;             MASK_BLOCK();
;             bool full = (kt == kt0);
;             float psa, psb;
;             if (!full) {
;                 EXPSUM_BLOCK();
;                 if (__any(psa + psb > 1.0e18f)) { full = true; QK_BLOCK();
.Lfb_s_top:
	s_bitcmp1_b32 s99, 0
	s_cselect_b32 s74, 0x5500, 0
	s_sub_i32 s75, 0x5500, s74
	v_exp_f32_e32 v106, v66
	v_exp_f32_e32 v124, v50
	v_exp_f32_e32 v107, v67
	v_exp_f32_e32 v125, v51
	v_add_f32_e32 v166, 0, v106
	v_add_f32_e32 v167, 0, v124
	v_exp_f32_e32 v108, v68
	v_exp_f32_e32 v126, v52
	v_add_f32_e32 v166, v107, v166
	v_add_f32_e32 v167, v125, v167
	v_exp_f32_e32 v109, v69
	v_exp_f32_e32 v127, v53
	v_add_f32_e32 v166, v108, v166
	v_add_f32_e32 v167, v126, v167
	v_exp_f32_e32 v110, v70
	v_exp_f32_e32 v128, v54
	v_add_f32_e32 v166, v109, v166
	v_add_f32_e32 v167, v127, v167
	v_exp_f32_e32 v111, v71
	v_exp_f32_e32 v129, v55
	v_add_f32_e32 v166, v110, v166
	v_add_f32_e32 v167, v128, v167
	v_exp_f32_e32 v112, v72
	v_exp_f32_e32 v130, v56
	v_add_f32_e32 v166, v111, v166
	v_add_f32_e32 v167, v129, v167
	v_exp_f32_e32 v113, v73
	v_exp_f32_e32 v131, v57
	v_add_f32_e32 v166, v112, v166
	v_add_f32_e32 v167, v130, v167
	v_exp_f32_e32 v116, v74
	v_exp_f32_e32 v132, v58
	v_add_f32_e32 v166, v113, v166
	v_add_f32_e32 v167, v131, v167
	v_exp_f32_e32 v117, v75
	v_exp_f32_e32 v133, v59
	v_add_f32_e32 v166, v116, v166
	v_add_f32_e32 v167, v132, v167
	v_exp_f32_e32 v118, v76
	v_exp_f32_e32 v134, v60
	v_add_f32_e32 v166, v117, v166
	v_add_f32_e32 v167, v133, v167
	v_exp_f32_e32 v119, v77
	v_exp_f32_e32 v135, v61
	v_add_f32_e32 v166, v118, v166
	v_add_f32_e32 v167, v134, v167
	v_exp_f32_e32 v120, v78
	v_exp_f32_e32 v136, v62
	v_add_f32_e32 v166, v119, v166
	v_add_f32_e32 v167, v135, v167
	v_exp_f32_e32 v121, v79
	v_exp_f32_e32 v137, v63
	v_add_f32_e32 v166, v120, v166
	v_add_f32_e32 v167, v136, v167
	v_exp_f32_e32 v122, v80
	v_exp_f32_e32 v138, v64
	v_add_f32_e32 v166, v121, v166
	v_add_f32_e32 v167, v137, v167
	v_exp_f32_e32 v123, v81
	v_exp_f32_e32 v139, v65
	v_add_f32_e32 v166, v122, v166
	v_add_f32_e32 v167, v138, v167
	s_nop 0
	v_add_f32_e32 v166, v123, v166
	v_add_f32_e32 v167, v139, v167
	v_add_f32_e32 v141, v166, v167
	v_cmp_lt_f32_e32 vcc, s85, v141
	s_cbranch_vccnz .Lfb_s_slow
; __device__ __forceinline__ s16x4 vtr(ldsp p) { return __builtin_bit_cast(s16x4, __builtin_amdgcn_ds_read_tr16_b64_v4i16((LAS v4i16_t*)p)); }
; template <bool DIFF>
; __device__ __forceinline__ void attn_unit(const AttnP& A, int b, int h, int qi, ldsp lds) {
;     ...
;             for (int t = 0; t < 2; ++t)
; #pragma unroll
;                 for (int j = 0; j < 4; ++j) {
;                     const bf16x8 vf = (bf16x8){vlo[t * 4 + j][0], vlo[t * 4 + j][1], vlo[t * 4 + j][2], vlo[t * 4 + j][3], vhi[t * 4 + j][0], vhi[t * 4 + j][1], vhi[t * 4 + j][2], vhi[t * 4 + j][3]};
;                     o[t] = __builtin_amdgcn_mfma_f32_32x32x16_bf16(vf, pw[j], o[t], 0, 0, 0);
;                 }
;             if (DIFF) {
; #pragma unroll
;                 for (int t = 2; t < NTD; ++t)
; #pragma unroll
;                     for (int j = 0; j < 4; ++j) { vlo[(t - 2) * 4 + j] = vtr(Vb + trb + (16 * j) * VP + t * 64); vhi[(t - 2) * 4 + j] = vtr(Vb + trb + (16 * j + 8) * VP + t * 64); }
;                 __builtin_amdgcn_sched_barrier(0);
; #pragma unroll
;                 for (int t = 2; t < NTD; ++t)
; #pragma unroll
;                     for (int j = 0; j < 4; ++j) {
;                         const int i = (t - 2) * 4 + j;
;                         const bf16x8 vf = (bf16x8){vlo[i][0], vlo[i][1], vlo[i][2], vlo[i][3], vhi[i][0], vhi[i][1], vhi[i][2], vhi[i][3]};
;                         o[t] = __builtin_amdgcn_mfma_f32_32x32x16_bf16(vf, pw[j], o[t], 0, 0, 0);
;                     }
;             }
;             __builtin_amdgcn_s_setprio(0);
	v_add_u32_e32 v169, s74, v150
	v_add_u32_e32 v0, s74, v164
	v_add_u32_e32 v168, s75, v161
	ds_read_b64_tr_b16 v[58:59], v168 offset:9216
	ds_read_b64_tr_b16 v[60:61], v168 offset:10752
	ds_read_b64_tr_b16 v[62:63], v168 offset:9280
	ds_read_b64_tr_b16 v[64:65], v168 offset:10816
	ds_read_b64_tr_b16 v[74:75], v168 offset:12288
	ds_read_b64_tr_b16 v[76:77], v168 offset:13824
	ds_read_b64_tr_b16 v[78:79], v168 offset:12352
	ds_read_b64_tr_b16 v[80:81], v168 offset:13888
	ds_read_b64_tr_b16 v[244:245], v168 offset:15360
	ds_read_b64_tr_b16 v[246:247], v168 offset:16896
	v_cvt_pk_bf16_f32 v66, v106, v107
	v_cvt_pk_bf16_f32 v67, v108, v109
	v_cvt_pk_bf16_f32 v68, v110, v111
	v_cvt_pk_bf16_f32 v69, v112, v113
	v_cvt_pk_bf16_f32 v70, v116, v117
	v_cvt_pk_bf16_f32 v71, v118, v119
	v_cvt_pk_bf16_f32 v72, v120, v121
	v_cvt_pk_bf16_f32 v73, v122, v123
	v_cvt_pk_bf16_f32 v50, v124, v125
	v_cvt_pk_bf16_f32 v51, v126, v127
	v_cvt_pk_bf16_f32 v52, v128, v129
	v_cvt_pk_bf16_f32 v53, v130, v131
	v_cvt_pk_bf16_f32 v54, v132, v133
	v_cvt_pk_bf16_f32 v55, v134, v135
	v_cvt_pk_bf16_f32 v56, v136, v137
	v_cvt_pk_bf16_f32 v57, v138, v139
	v_add_f32_e32 v154, v141, v154
	ds_read_b64_tr_b16 v[106:107], v168 offset:15424
	ds_read_b64_tr_b16 v[108:109], v168 offset:16960
	ds_read_b64_tr_b16 v[110:111], v168 offset:18432
	ds_read_b64_tr_b16 v[112:113], v168 offset:19968
	ds_read_b64_tr_b16 v[116:117], v168 offset:18496
	ds_read_b64_tr_b16 v[118:119], v168 offset:20032
	v_mov_b32_e32 v248, s97
	ds_read_b32 v248, v248
	ds_read_b128 v[120:123], v169
	ds_read_b128 v[124:127], v169 offset:4608
	ds_read_b128 v[128:131], v169 offset:32
	ds_read_b128 v[132:135], v169 offset:4640
	ds_read_b128 v[136:139], v169 offset:64
	ds_read_b128 v[170:173], v169 offset:4672
	s_setprio 1
	s_waitcnt lgkmcnt(15)
	v_mfma_f32_32x32x16_bf16 v[18:33], v[58:61], v[66:69], v[18:33]
	v_mfma_f32_32x32x16_bf16 v[2:17], v[62:65], v[66:69], v[2:17]
	v_mfma_f32_32x32x16_bf16 v[18:33], v[74:77], v[70:73], v[18:33]
	v_mfma_f32_32x32x16_bf16 v[2:17], v[78:81], v[70:73], v[2:17]
	s_waitcnt lgkmcnt(13)
	v_mfma_f32_32x32x16_bf16 v[18:33], v[244:247], v[50:53], v[18:33]
	ds_read_b128 v[244:247], v169 offset:96
	s_waitcnt lgkmcnt(12)
	v_mfma_f32_32x32x16_bf16 v[2:17], v[106:109], v[50:53], v[2:17]
	ds_read_b128 v[106:109], v169 offset:4704
	s_waitcnt lgkmcnt(11)
	v_mfma_f32_32x32x16_bf16 v[18:33], v[110:113], v[54:57], v[18:33]
	ds_read_b128 v[110:113], v0 offset:128
	s_waitcnt lgkmcnt(10)
	v_mfma_f32_32x32x16_bf16 v[2:17], v[116:119], v[54:57], v[2:17]
	ds_read_b128 v[116:119], v0 offset:4736
	s_waitcnt lgkmcnt(9)
	v_mfma_f32_32x32x16_bf16 v[66:81], v[120:123], v[90:93], v[34:49]
	s_waitcnt lgkmcnt(8)
	v_mfma_f32_32x32x16_bf16 v[50:65], v[124:127], v[90:93], v[34:49]
	v_sub_f32_e32 v249, v160, v248
	v_cvt_pk_bf16_f32 v162, v249, 0
	v_lshlrev_b32_e32 v162, 16, v162
	s_waitcnt lgkmcnt(7)
	v_mfma_f32_32x32x16_bf16 v[66:81], v[128:131], v[82:85], v[66:81]
	s_waitcnt lgkmcnt(6)
	v_mfma_f32_32x32x16_bf16 v[50:65], v[132:135], v[82:85], v[50:65]
	v_sub_f32_e32 v249, v249, v162
	v_cvt_pk_bf16_f32 v163, v249, 0
	v_and_b32_e32 v157, 0xffff, v163
	v_lshlrev_b32_e32 v163, 16, v163
	s_waitcnt lgkmcnt(5)
	v_mfma_f32_32x32x16_bf16 v[66:81], v[136:139], v[86:89], v[66:81]
	s_waitcnt lgkmcnt(4)
	v_mfma_f32_32x32x16_bf16 v[50:65], v[170:173], v[86:89], v[50:65]
	v_sub_f32_e32 v249, v249, v163
	v_cvt_pk_bf16_f32 v249, v249, 0
	v_or_b32_e32 v162, 0x3f80, v162
	v_lshl_or_b32 v249, v249, 16, v157
	v_cndmask_b32_e64 v140, 0, v114, s[46:47]
	v_cndmask_b32_e64 v142, 0, v249, s[46:47]
	v_cndmask_b32_e64 v141, 0, v162, s[46:47]
	v_mov_b32_e32 v143, v1
	s_waitcnt lgkmcnt(3)
	v_mfma_f32_32x32x16_bf16 v[66:81], v[244:247], v[94:97], v[66:81]
	s_waitcnt lgkmcnt(2)
	v_mfma_f32_32x32x16_bf16 v[50:65], v[106:109], v[94:97], v[50:65]
	s_waitcnt lgkmcnt(1)
	v_mfma_f32_32x32x16_bf16 v[66:81], v[110:113], v[140:143], v[66:81]
	s_waitcnt lgkmcnt(0)
	v_mfma_f32_32x32x16_bf16 v[50:65], v[116:119], v[140:143], v[50:65]
	s_setprio 0
	s_waitcnt vmcnt(0)
	v_add_u32_e32 v115, s75, v156
	ds_write_b128 v115, v[98:101]
	s_and_saveexec_b64 s[0:1], s[44:45]
	v_xor_b32_e32 v248, 0x80000000, v155
	v_cvt_pk_bf16_f32 v248, v248, 0
	v_lshlrev_b32_e32 v249, 16, v248
	v_sub_f32_e64 v249, -v155, v249
	v_cvt_pk_bf16_f32 v162, v249, 0
	v_lshlrev_b32_e32 v162, 16, v162
	v_sub_f32_e32 v249, v249, v162
	v_cvt_pk_bf16_f32 v249, v249, 0
	v_and_or_b32 v112, v248, s83, v162
	v_and_or_b32 v113, v249, s83, 1.0
	v_mov_b32_e32 v115, v1
	v_add_u32_e32 v248, s75, v159
	ds_write_b128 v248, v[112:115] offset:128
	s_mov_b64 exec, s[0:1]
	v_add_u32_e32 v115, s74, v158
	ds_write_b128 v115, v[102:105] offset:9216
	global_load_dwordx4 v[102:105], v[250:251], off
	v_lshl_add_u64 v[250:251], v[250:251], 0, s[26:27]
	global_load_dwordx4 v[98:101], v[152:153], off
	v_lshl_add_u64 v[152:153], v[152:153], 0, s[26:27]
	s_and_saveexec_b64 s[0:1], s[44:45]
	global_load_dword v155, v[252:253], off
	s_mov_b64 exec, s[0:1]
	s_mov_b64 s[0:1], 0x800
	v_lshl_add_u64 v[252:253], v[252:253], 0, s[0:1]
	s_waitcnt lgkmcnt(0)
	s_barrier
	s_add_i32 s99, s99, 1
	s_add_i32 s94, s94, 1
	s_add_i32 s97, s97, 4
	s_add_i32 s98, s98, 64
	s_add_i32 s0, s95, 0
	s_cmp_le_i32 s99, s0
	s_cbranch_scc1 .Lfb_s_top

; __device__ __forceinline__ unsigned cvtpk(float lo, float hi) { f32x2 v = {lo, hi}; bf16x2_t b = __builtin_convertvector(v, bf16x2_t); return __builtin_bit_cast(unsigned, b); }
; template <bool DIFF>
; __device__ __forceinline__ void attn_unit(const AttnP& A, int b, int h, int qi, ldsp lds) {
;     ...
;             bf16x8 pw[4];
; #pragma unroll
;             for (int j = 0; j < 4; ++j) {
;                 u32x4 pk;
;                 if (j < 2) { const int rb = 8 * (j & 1); pk.x = cvtpk(s0[rb], s0[rb + 1]); pk.y = cvtpk(s0[rb + 2], s0[rb + 3]); pk.z = cvtpk(s0[rb + 4], s0[rb + 5]); pk.w = cvtpk(s0[rb + 6], s0[rb + 7]); }
;                 else { const int rb = 8 * (j & 1); pk.x = cvtpk(s1[rb], s1[rb + 1]); pk.y = cvtpk(s1[rb + 2], s1[rb + 3]); pk.z = cvtpk(s1[rb + 4], s1[rb + 5]); pk.w = cvtpk(s1[rb + 6], s1[rb + 7]); }
;                 pw[j] = __builtin_bit_cast(bf16x8, pk);
;             }
;             __builtin_amdgcn_sched_barrier(0);
;             __builtin_amdgcn_s_setprio(1);
; #pragma unroll
;             for (int t = 0; t < 2; ++t)
; #pragma unroll
;                 for (int j = 0; j < 4; ++j) {
;                     const bf16x8 vf = (bf16x8){vlo[t * 4 + j][0], vlo[t * 4 + j][1], vlo[t * 4 + j][2], vlo[t * 4 + j][3], vhi[t * 4 + j][0], vhi[t * 4 + j][1], vhi[t * 4 + j][2], vhi[t * 4 + j][3]};
;                     o[t] = __builtin_amdgcn_mfma_f32_32x32x16_bf16(vf, pw[j], o[t], 0, 0, 0);
;                 }
;             if (DIFF) {
; #pragma unroll
;                 for (int t = 2; t < NTD; ++t)
; #pragma unroll
;                     for (int j = 0; j < 4; ++j) { vlo[(t - 2) * 4 + j] = vtr(Vb + trb + (16 * j) * VP + t * 64); vhi[(t - 2) * 4 + j] = vtr(Vb + trb + (16 * j + 8) * VP + t * 64); }
;                 __builtin_amdgcn_sched_barrier(0);
; #pragma unroll
;                 for (int t = 2; t < NTD; ++t)
; #pragma unroll
;                     for (int j = 0; j < 4; ++j) {
;                         const int i = (t - 2) * 4 + j;
;                         const bf16x8 vf = (bf16x8){vlo[i][0], vlo[i][1], vlo[i][2], vlo[i][3], vhi[i][0], vhi[i][1], vhi[i][2], vhi[i][3]};
;                         o[t] = __builtin_amdgcn_mfma_f32_32x32x16_bf16(vf, pw[j], o[t], 0, 0, 0);
;                     }
;             }
;             __builtin_amdgcn_s_setprio(0);
.Lfx14_pack:
	v_add_u32_e32 v169, s74, v150
	v_add_u32_e32 v0, s74, v164
	v_add_u32_e32 v168, s75, v161
	ds_read_b64_tr_b16 v[58:59], v168 offset:9216
	ds_read_b64_tr_b16 v[60:61], v168 offset:10752
	ds_read_b64_tr_b16 v[62:63], v168 offset:9280
	ds_read_b64_tr_b16 v[64:65], v168 offset:10816
	ds_read_b64_tr_b16 v[74:75], v168 offset:12288
	ds_read_b64_tr_b16 v[76:77], v168 offset:13824
	ds_read_b64_tr_b16 v[78:79], v168 offset:12352
	ds_read_b64_tr_b16 v[80:81], v168 offset:13888
	ds_read_b64_tr_b16 v[244:245], v168 offset:15360
	ds_read_b64_tr_b16 v[246:247], v168 offset:16896
	v_add_f32_e32 v141, v167, v166
	v_cvt_pk_bf16_f32 v66, v106, v107
	v_cvt_pk_bf16_f32 v67, v108, v109
	v_cvt_pk_bf16_f32 v68, v110, v111
	v_cvt_pk_bf16_f32 v69, v112, v113
	v_cvt_pk_bf16_f32 v70, v116, v117
	v_cvt_pk_bf16_f32 v71, v118, v119
	v_cvt_pk_bf16_f32 v72, v120, v121
	v_cvt_pk_bf16_f32 v73, v122, v123
	v_cvt_pk_bf16_f32 v50, v124, v125
	v_cvt_pk_bf16_f32 v51, v126, v127
	v_cvt_pk_bf16_f32 v52, v128, v129
	v_cvt_pk_bf16_f32 v53, v130, v131
	v_cvt_pk_bf16_f32 v54, v132, v133
	v_cvt_pk_bf16_f32 v55, v134, v135
	v_cvt_pk_bf16_f32 v56, v136, v137
	v_cvt_pk_bf16_f32 v57, v138, v139
	v_add_f32_e32 v154, v141, v154
	ds_read_b64_tr_b16 v[106:107], v168 offset:15424
	ds_read_b64_tr_b16 v[108:109], v168 offset:16960
	ds_read_b64_tr_b16 v[110:111], v168 offset:18432
	ds_read_b64_tr_b16 v[112:113], v168 offset:19968
	ds_read_b64_tr_b16 v[116:117], v168 offset:18496
	ds_read_b64_tr_b16 v[118:119], v168 offset:20032
	s_cmp_eq_u32 s99, s64
	s_cbranch_scc1 .Lfb_last
	v_mov_b32_e32 v248, s97
	ds_read_b32 v248, v248
	ds_read_b128 v[120:123], v169
	ds_read_b128 v[124:127], v169 offset:4608
	ds_read_b128 v[128:131], v169 offset:32
	ds_read_b128 v[132:135], v169 offset:4640
	ds_read_b128 v[136:139], v169 offset:64
	ds_read_b128 v[170:173], v169 offset:4672
	s_setprio 1
	s_waitcnt lgkmcnt(15)
	v_mfma_f32_32x32x16_bf16 v[18:33], v[58:61], v[66:69], v[18:33]
	v_mfma_f32_32x32x16_bf16 v[2:17], v[62:65], v[66:69], v[2:17]
	v_mfma_f32_32x32x16_bf16 v[18:33], v[74:77], v[70:73], v[18:33]
	v_mfma_f32_32x32x16_bf16 v[2:17], v[78:81], v[70:73], v[2:17]
	s_waitcnt lgkmcnt(13)
	v_mfma_f32_32x32x16_bf16 v[18:33], v[244:247], v[50:53], v[18:33]
	ds_read_b128 v[244:247], v169 offset:96
	s_waitcnt lgkmcnt(12)
	v_mfma_f32_32x32x16_bf16 v[2:17], v[106:109], v[50:53], v[2:17]
	ds_read_b128 v[106:109], v169 offset:4704
	s_waitcnt lgkmcnt(11)
	v_mfma_f32_32x32x16_bf16 v[18:33], v[110:113], v[54:57], v[18:33]
	ds_read_b128 v[110:113], v0 offset:128
	s_waitcnt lgkmcnt(10)
	v_mfma_f32_32x32x16_bf16 v[2:17], v[116:119], v[54:57], v[2:17]
	ds_read_b128 v[116:119], v0 offset:4736
	s_waitcnt lgkmcnt(9)
	v_mfma_f32_32x32x16_bf16 v[66:81], v[120:123], v[90:93], v[34:49]
	s_waitcnt lgkmcnt(8)
	v_mfma_f32_32x32x16_bf16 v[50:65], v[124:127], v[90:93], v[34:49]
	v_sub_f32_e32 v249, v160, v248
	v_cvt_pk_bf16_f32 v162, v249, 0
	v_lshlrev_b32_e32 v162, 16, v162
	s_waitcnt lgkmcnt(7)
	v_mfma_f32_32x32x16_bf16 v[66:81], v[128:131], v[82:85], v[66:81]
	s_waitcnt lgkmcnt(6)
	v_mfma_f32_32x32x16_bf16 v[50:65], v[132:135], v[82:85], v[50:65]
	v_sub_f32_e32 v249, v249, v162
	v_cvt_pk_bf16_f32 v163, v249, 0
	v_and_b32_e32 v157, 0xffff, v163
	v_lshlrev_b32_e32 v163, 16, v163
	s_waitcnt lgkmcnt(5)
	v_mfma_f32_32x32x16_bf16 v[66:81], v[136:139], v[86:89], v[66:81]
	s_waitcnt lgkmcnt(4)
	v_mfma_f32_32x32x16_bf16 v[50:65], v[170:173], v[86:89], v[50:65]
	v_sub_f32_e32 v249, v249, v163
	v_cvt_pk_bf16_f32 v249, v249, 0
	v_or_b32_e32 v162, 0x3f80, v162
	v_lshl_or_b32 v249, v249, 16, v157
	v_cndmask_b32_e64 v140, 0, v114, s[46:47]
	v_cndmask_b32_e64 v142, 0, v249, s[46:47]
	v_cndmask_b32_e64 v141, 0, v162, s[46:47]
	v_mov_b32_e32 v143, v1
	s_waitcnt lgkmcnt(3)
	v_mfma_f32_32x32x16_bf16 v[66:81], v[244:247], v[94:97], v[66:81]
	s_waitcnt lgkmcnt(2)
	v_mfma_f32_32x32x16_bf16 v[50:65], v[106:109], v[94:97], v[50:65]
	s_waitcnt lgkmcnt(1)
	v_mfma_f32_32x32x16_bf16 v[66:81], v[110:113], v[140:143], v[66:81]
	s_waitcnt lgkmcnt(0)
	v_mfma_f32_32x32x16_bf16 v[50:65], v[116:119], v[140:143], v[50:65]
	s_setprio 0
	s_branch .Lfb_stores
.Lfb_last:
	s_setprio 1
	s_waitcnt lgkmcnt(14)
	v_mfma_f32_32x32x16_bf16 v[18:33], v[58:61], v[66:69], v[18:33]
	s_waitcnt lgkmcnt(12)
	v_mfma_f32_32x32x16_bf16 v[2:17], v[62:65], v[66:69], v[2:17]
	s_waitcnt lgkmcnt(10)
	v_mfma_f32_32x32x16_bf16 v[18:33], v[74:77], v[70:73], v[18:33]
	s_waitcnt lgkmcnt(8)
	v_mfma_f32_32x32x16_bf16 v[2:17], v[78:81], v[70:73], v[2:17]
	s_waitcnt lgkmcnt(6)
	v_mfma_f32_32x32x16_bf16 v[18:33], v[244:247], v[50:53], v[18:33]
	s_waitcnt lgkmcnt(4)
	v_mfma_f32_32x32x16_bf16 v[2:17], v[106:109], v[50:53], v[2:17]
	s_waitcnt lgkmcnt(2)
	v_mfma_f32_32x32x16_bf16 v[18:33], v[110:113], v[54:57], v[18:33]
	s_waitcnt lgkmcnt(0)
	v_mfma_f32_32x32x16_bf16 v[2:17], v[116:119], v[54:57], v[2:17]
	s_setprio 0
	s_branch .Lfb_stores
.Lfb_first:
	v_add_u32_e32 v169, s74, v150
	v_add_u32_e32 v0, s74, v164
	ds_read_b128 v[106:109], v169
	ds_read_b128 v[110:113], v169 offset:4608
	ds_read_b128 v[116:119], v169 offset:32
	ds_read_b128 v[120:123], v169 offset:4640
	ds_read_b128 v[124:127], v169 offset:64
	ds_read_b128 v[128:131], v169 offset:4672
	ds_read_b128 v[132:135], v169 offset:96
	ds_read_b128 v[136:139], v169 offset:4704
	v_mov_b32_e32 v248, s97
	ds_read_b32 v248, v248
	ds_read_b128 v[170:173], v0 offset:128
	ds_read_b128 v[244:247], v0 offset:4736
	s_setprio 1
	s_waitcnt lgkmcnt(10)
	v_mfma_f32_32x32x16_bf16 v[66:81], v[106:109], v[90:93], v[34:49]
	s_waitcnt lgkmcnt(9)
	v_mfma_f32_32x32x16_bf16 v[50:65], v[110:113], v[90:93], v[34:49]
	s_waitcnt lgkmcnt(2)
	v_sub_f32_e32 v249, v160, v248
	v_cvt_pk_bf16_f32 v162, v249, 0
	v_lshlrev_b32_e32 v162, 16, v162
	v_mfma_f32_32x32x16_bf16 v[66:81], v[116:119], v[82:85], v[66:81]
	v_mfma_f32_32x32x16_bf16 v[50:65], v[120:123], v[82:85], v[50:65]
	v_sub_f32_e32 v249, v249, v162
	v_cvt_pk_bf16_f32 v163, v249, 0
	v_and_b32_e32 v157, 0xffff, v163
	v_lshlrev_b32_e32 v163, 16, v163
	v_mfma_f32_32x32x16_bf16 v[66:81], v[124:127], v[86:89], v[66:81]
	v_mfma_f32_32x32x16_bf16 v[50:65], v[128:131], v[86:89], v[50:65]
	v_sub_f32_e32 v249, v249, v163
	v_cvt_pk_bf16_f32 v249, v249, 0
	v_or_b32_e32 v162, 0x3f80, v162
	v_lshl_or_b32 v249, v249, 16, v157
	v_cndmask_b32_e64 v140, 0, v114, s[46:47]
	v_cndmask_b32_e64 v142, 0, v249, s[46:47]
	v_cndmask_b32_e64 v141, 0, v162, s[46:47]
	v_mov_b32_e32 v143, v1
	v_mfma_f32_32x32x16_bf16 v[66:81], v[132:135], v[94:97], v[66:81]
	v_mfma_f32_32x32x16_bf16 v[50:65], v[136:139], v[94:97], v[50:65]
	s_waitcnt lgkmcnt(1)
	v_mfma_f32_32x32x16_bf16 v[66:81], v[170:173], v[140:143], v[66:81]
	s_waitcnt lgkmcnt(0)
	v_mfma_f32_32x32x16_bf16 v[50:65], v[244:247], v[140:143], v[50:65]
	s_setprio 0
